# NSA near-tile bias/mask via per-head sentinel table in LDS (ds_read2 + add, no compares/selects); on top of k17
# speedup vs baseline: 1.0252x; 1.0252x over previous
; #define LAS __attribute__((address_space(3)))
; DI int opaque_tid(int wv) { unsigned ones = ~0u; asm volatile("" : "+s"(ones)); int t = wv * 64 + (int)__builtin_amdgcn_mbcnt_hi(ones, __builtin_amdgcn_mbcnt_lo(ones, 0u)); asm volatile("" : "+v"(t)); return t; }
; DI void nsa_attn_phase(int wv, LAS unsigned char* lds, const bf16_t* Q, const bf16_t* slab, const bf16_t* VT2, const float* gates, const bf16_t* KCMP, const bf16_t* VCMPT,
;                        const float* rel_bias, bf16_t* O) {
;     ...
;         const int b = item >> 4, g = (item >> 2) & 3, qtr = item & 3;
;         const int head = g * 4 + rhead;
;         const size_t bg = (size_t)(b * 4 + g);
;         int tid = opaque_tid(wv), lane = tid & 63;
;         __syncthreads();
; #pragma unroll
;         for (int e = 0; e < 2; ++e) { const int pc = tid + 512 * e;
;             const u32x4 v = *(const u32x4*)(KCMP + bg * 128 * 64 + (size_t)pc * 8); *(LAS u32x4*)(lds + OFF_KC + (pc >> 3) * KCS + (pc & 7) * 16) = v;
;             const u32x4 v2 = *(const u32x4*)(VCMPT + bg * 64 * 128 + (size_t)pc * 8); lds_store16_as2x8(lds + OFF_VC + (pc >> 4) * VCS + (pc & 15) * 16, v2); }
;         lut[tid] = rel_bias[t5_bucket(tid & 127) * 16 + g * 4 + (tid >> 7)] * LOG2E;
;         __syncthreads();
;         const LAS float* mylut = lut + rhead * 128;
.LBB0_2238:
	s_or_b64 exec, exec, s[6:7]
	s_lshl_b32 s6, s0, 2
	v_lshlrev_b32_e32 v0, 4, v0
	v_ashrrev_i32_e32 v3, 7, v2
	v_add3_u32 v4, s6, v3, v0
	v_readlane_b32 s16, v254, 2
	v_ashrrev_i32_e32 v5, 31, v4
	v_readlane_b32 s22, v254, 8
	v_readlane_b32 s23, v254, 9
	v_readlane_b32 s17, v254, 3
	s_and_b32 s66, s1, 3
	v_lshl_add_u64 v[4:5], v[4:5], 2, s[22:23]
	global_load_dword v0, v[4:5], off
	s_ashr_i32 s3, s2, 31
	s_or_b32 s1, s6, s56
	v_readlane_b32 s18, v254, 4
	s_xor_b32 s67, s66, 3
	s_lshl_b64 s[16:17], s[2:3], 11
	s_lshl_b32 s6, s1, 7
	v_readlane_b32 s19, v254, 5
	s_add_u32 s18, s38, s6
	v_readlane_b32 s20, v254, 6
	s_mul_i32 s1, s1, 12
	s_addc_u32 s19, s39, 0
	v_readlane_b32 s21, v254, 7
	s_add_u32 s20, s48, s1
	s_addc_u32 s21, s49, 0
	s_lshl_b64 s[4:5], s[4:5], 18
	s_add_u32 s69, s46, s4
	s_addc_u32 s84, s47, s5
	s_lshl_b64 s[22:23], s[2:3], 9
	s_lshl_b32 s0, s0, 6
	v_readlane_b32 s24, v254, 10
	s_or_b32 s22, s22, s0
	v_readlane_b32 s25, v254, 11
	v_lshl_add_u32 v2, v2, 2, 0
	s_add_u32 s24, s44, s6
	v_add_u32_e32 v2, 0x1a300, v2
	s_addc_u32 s25, s45, 0
	s_mov_b32 s85, 0
	v_readlane_b32 s26, v254, 12
	v_readlane_b32 s27, v254, 13
	v_readlane_b32 s28, v254, 14
	v_readlane_b32 s29, v254, 15
	v_readlane_b32 s30, v254, 16
	v_readlane_b32 s31, v254, 17
	s_waitcnt vmcnt(0)
	v_mul_f32_e32 v0, 0x3fb8aa3b, v0
	ds_write_b32 v2, v0
	s_waitcnt lgkmcnt(0)
	s_barrier
	s_mov_b32 s0, -1
	v_mbcnt_lo_u32_b32 v0, s0, 0
	v_mbcnt_hi_u32_b32 v0, s0, v0
	v_add_u32_e32 v2, s11, v0
	v_subrev_u32_e32 v3, 64, v2
	v_mov_b32_e32 v5, 0x7f
	v_med3_i32 v4, v3, 0, v5
	v_lshlrev_b32_e32 v4, 2, v4
	v_lshlrev_b32_e32 v6, 2, v2
	v_mov_b32_e32 v9, 0xf149f2ca
	v_add_u32_e32 v7, 0x1a300, v4
	ds_read_b32 v10, v7
	v_add_u32_e32 v7, 0x1a500, v4
	ds_read_b32 v11, v7
	v_add_u32_e32 v7, 0x1a700, v4
	ds_read_b32 v12, v7
	v_add_u32_e32 v7, 0x1a900, v4
	ds_read_b32 v13, v7
	v_cmp_gt_i32_e32 vcc, 0, v3
	s_waitcnt lgkmcnt(0)
	v_cndmask_b32_e32 v10, v10, v9, vcc
	v_add_u32_e32 v7, 0x1ab00, v6
	ds_write_b32 v7, v10
	v_cndmask_b32_e32 v11, v11, v9, vcc
	v_add_u32_e32 v7, 0x1b600, v6
	ds_write_b32 v7, v11
	v_cndmask_b32_e32 v12, v12, v9, vcc
	v_add_u32_e32 v7, 0x1c100, v6
	ds_write_b32 v7, v12
	v_cndmask_b32_e32 v13, v13, v9, vcc
	v_add_u32_e32 v7, 0x1cc00, v6
	ds_write_b32 v7, v13
	v_cmp_gt_u32_e32 vcc, 0xc0, v2
	s_and_saveexec_b64 s[0:1], vcc
	v_mov_b32_e32 v7, 0x1a4fc
	ds_read_b32 v10, v7
	v_mov_b32_e32 v7, 0x1a6fc
	ds_read_b32 v11, v7
	v_mov_b32_e32 v7, 0x1a8fc
	ds_read_b32 v12, v7
	v_mov_b32_e32 v7, 0x1aafc
	ds_read_b32 v13, v7
	v_cmp_gt_u32_e32 vcc, 64, v2
	s_waitcnt lgkmcnt(0)
	v_cndmask_b32_e32 v10, v9, v10, vcc
	v_add_u32_e32 v7, 0x1b300, v6
	ds_write_b32 v7, v10
	v_cndmask_b32_e32 v11, v9, v11, vcc
	v_add_u32_e32 v7, 0x1be00, v6
	ds_write_b32 v7, v11
	v_cndmask_b32_e32 v12, v9, v12, vcc
	v_add_u32_e32 v7, 0x1c900, v6
	ds_write_b32 v7, v12
	v_cndmask_b32_e32 v13, v9, v13, vcc
	v_add_u32_e32 v7, 0x1d400, v6
	ds_write_b32 v7, v13
	s_or_b64 exec, exec, s[0:1]
	s_sub_i32 s70, s57, 0x1a300
	s_mul_i32 s70, s70, 11
	s_lshr_b32 s70, s70, 1
	s_add_i32 s70, s70, 0x1aa14
	s_waitcnt lgkmcnt(0)
	s_barrier
	s_branch .LBB0_2240

; #define LAS __attribute__((address_space(3)))
; DI void nsa_attn_phase(int wv, LAS unsigned char* lds, const bf16_t* Q, const bf16_t* slab, const bf16_t* VT2, const float* gates, const bf16_t* KCMP, const bf16_t* VCMPT,
;                        const float* rel_bias, bf16_t* O) {
;     ...
;                 auto process = [&](const LAS unsigned char* kb, int j) {
;                     const int k0 = 64 * j;
;                     const bool selbit = (br == 0) ? (((mysel >> j) & 1u) != 0u) : true;
;                     if (br == 0 && __ballot(selbit) == 0ull) return;
;                     const bool far = (TW - (k0 + 63) >= 127) && (br == 0 || (TW + 31 - k0 < 512));
;                     f32x16 s[2];
;                     qk_tile<4>(kb, KS, qf, s, r, hh, ref_frag(-m, far ? (selbit ? c31 : NEGF) : 0.f, hh));
;                     if (!far) {
;                         const int d0 = tq - k0 - 4 * hh;
; #pragma unroll
;                         for (int t = 0; t < 2; ++t)
; #pragma unroll
;                             for (int i = 0; i < 16; ++i) {
;                                 const int dist = d0 - (32 * t + (i & 3) + 8 * (i >> 2));
;                                 const float bias = mylut[dist < 0 ? 0 : (dist > 127 ? 127 : dist)];
;                                 const bool valid = selbit && dist >= 0 && (br == 0 || dist < 512);
;                                 s[t][i] = valid ? s[t][i] + bias : NEGF;
;                             }
.LBB0_2427:
	s_andn2_b64 vcc, exec, s[6:7]
	s_cbranch_vccnz .LBB0_2420
	s_mulk_i32 s0, 0x4600
	s_add_i32 s0, s0, 0
	v_cvt_pk_bf16_f32 v3, -v4, s0
	v_perm_b32 v3, 0, v3, v229
	v_lshlrev_b32_e32 v7, 16, v3
	v_sub_f32_e64 v7, -v4, v7
	v_cvt_pk_bf16_f32 v7, v7, s0
	v_mul_i32_i24_e32 v0, 0xffffffc0, v144
	v_lshl_or_b32 v3, v7, 16, v3
	v_add3_u32 v7, s0, v212, v241
	v_add_u32_e32 v2, s92, v0
	s_movk_i32 s1, 0x7e
	ds_read_b128 v[8:11], v7 offset:35328
	ds_read_b128 v[12:15], v7 offset:35360
	ds_read_b128 v[144:147], v7 offset:35392
	ds_read_b128 v[148:151], v7 offset:35424
	v_cmp_lt_i32_e64 s[6:7], s1, v2
	v_add_u32_e32 v2, s93, v0
	v_cmp_gt_i32_e32 vcc, s83, v2
	s_or_b64 s[30:31], s[8:9], vcc
	s_or_b64 vcc, s[26:27], s[4:5]
	v_mov_b32_e32 v2, 0xfffff14a
	v_cndmask_b32_e32 v2, v2, v240, vcc
	s_and_b64 s[4:5], s[6:7], s[30:31]
	v_cndmask_b32_e64 v2, 0, v2, s[4:5]
	v_mov_b32_e32 v208, 0x1100
	v_perm_b32 v2, 0, v2, v229
	s_xor_b64 s[4:5], s[4:5], -1
	v_cndmask_b32_e64 v246, 0, v3, s[2:3]
	v_cndmask_b32_e64 v247, 0, v2, s[2:3]
	v_mov_b32_e32 v248, v1
	v_mov_b32_e32 v249, v1
	s_waitcnt lgkmcnt(0)
	v_mfma_f32_32x32x16_bf16 v[160:175], v[8:11], v[176:179], 0
	v_mfma_f32_32x32x16_bf16 v[160:175], v[12:15], v[180:183], v[160:175]
	ds_read_b128 v[8:11], v7 offset:39936
	ds_read_b128 v[12:15], v7 offset:39968
	ds_read_b128 v[250:253], v7 offset:40000
	ds_read_b128 v[224:227], v7 offset:40032
	v_mfma_f32_32x32x16_bf16 v[160:175], v[144:147], v[184:187], v[160:175]
	v_mfma_f32_32x32x16_bf16 v[160:175], v[148:151], v[188:191], v[160:175]
	v_mfma_f32_32x32x16_bf16 v[160:175], v[192:195], v[246:249], v[160:175]
	s_waitcnt lgkmcnt(0)
	v_mfma_f32_32x32x16_bf16 v[144:159], v[8:11], v[176:179], 0
	v_mfma_f32_32x32x16_bf16 v[144:159], v[12:15], v[180:183], v[144:159]
	v_mfma_f32_32x32x16_bf16 v[144:159], v[250:253], v[184:187], v[144:159]
	v_mfma_f32_32x32x16_bf16 v[144:159], v[224:227], v[188:191], v[144:159]
	v_mfma_f32_32x32x16_bf16 v[144:159], v[192:195], v[246:249], v[144:159]
	s_and_saveexec_b64 s[6:7], s[4:5]
	s_cbranch_execz .LBB0_2430
	v_add_u32_e32 v2, v0, v210
	v_sub_u32_e32 v2, v2, v233
	v_add_u32_e32 v2, 64, v2
	v_mov_b32_e32 v3, 63
	v_cndmask_b32_e32 v2, v3, v2, vcc
	v_lshl_add_u32 v2, v2, 2, s70
	ds_read2_b32 v[20:21], v2 offset0:59 offset1:58
	ds_read2_b32 v[22:23], v2 offset0:57 offset1:56
	ds_read2_b32 v[24:25], v2 offset0:51 offset1:50
	ds_read2_b32 v[26:27], v2 offset0:49 offset1:48
	ds_read2_b32 v[28:29], v2 offset0:43 offset1:42
	ds_read2_b32 v[30:31], v2 offset0:41 offset1:40
	ds_read2_b32 v[32:33], v2 offset0:35 offset1:34
	ds_read2_b32 v[34:35], v2 offset0:33 offset1:32
	ds_read2_b32 v[36:37], v2 offset0:27 offset1:26
	ds_read2_b32 v[38:39], v2 offset0:25 offset1:24
	ds_read2_b32 v[40:41], v2 offset0:19 offset1:18
	ds_read2_b32 v[42:43], v2 offset0:17 offset1:16
	ds_read2_b32 v[44:45], v2 offset0:11 offset1:10
	ds_read2_b32 v[46:47], v2 offset0:9 offset1:8
	ds_read2_b32 v[48:49], v2 offset0:3 offset1:2
	ds_read2_b32 v[50:51], v2 offset0:1 offset1:0
	s_waitcnt lgkmcnt(15)
	v_add_f32_e32 v160, v160, v20
	v_add_f32_e32 v161, v161, v21
	s_waitcnt lgkmcnt(14)
	v_add_f32_e32 v162, v162, v22
	v_add_f32_e32 v163, v163, v23
	s_waitcnt lgkmcnt(13)
	v_add_f32_e32 v164, v164, v24
	v_add_f32_e32 v165, v165, v25
	s_waitcnt lgkmcnt(12)
	v_add_f32_e32 v166, v166, v26
	v_add_f32_e32 v167, v167, v27
	s_waitcnt lgkmcnt(11)
	v_add_f32_e32 v168, v168, v28
	v_add_f32_e32 v169, v169, v29
	s_waitcnt lgkmcnt(10)
	v_add_f32_e32 v170, v170, v30
	v_add_f32_e32 v171, v171, v31
	s_waitcnt lgkmcnt(9)
	v_add_f32_e32 v172, v172, v32
	v_add_f32_e32 v173, v173, v33
	s_waitcnt lgkmcnt(8)
	v_add_f32_e32 v174, v174, v34
	v_add_f32_e32 v175, v175, v35
	s_waitcnt lgkmcnt(7)
	v_add_f32_e32 v144, v144, v36
	v_add_f32_e32 v145, v145, v37
	s_waitcnt lgkmcnt(6)
	v_add_f32_e32 v146, v146, v38
	v_add_f32_e32 v147, v147, v39
	s_waitcnt lgkmcnt(5)
	v_add_f32_e32 v148, v148, v40
	v_add_f32_e32 v149, v149, v41
	s_waitcnt lgkmcnt(4)
	v_add_f32_e32 v150, v150, v42
	v_add_f32_e32 v151, v151, v43
	s_waitcnt lgkmcnt(3)
	v_add_f32_e32 v152, v152, v44
	v_add_f32_e32 v153, v153, v45
	s_waitcnt lgkmcnt(2)
	v_add_f32_e32 v154, v154, v46
	v_add_f32_e32 v155, v155, v47
	s_waitcnt lgkmcnt(1)
	v_add_f32_e32 v156, v156, v48
	v_add_f32_e32 v157, v157, v49
	s_waitcnt lgkmcnt(0)
	v_add_f32_e32 v158, v158, v50
	v_add_f32_e32 v159, v159, v51
